# per-tile accumulator clears in the 12 GEMM loops use 64 v_mov_b64 instead of 128 v_mov_b32
# speedup vs baseline: 1.0030x; 1.0030x over previous
.LBB0_486:
	v_mov_b64_e32 v[2:3], 0
	v_mov_b64_e32 v[4:5], 0
	v_mov_b64_e32 v[6:7], 0
	v_mov_b64_e32 v[8:9], 0
	v_mov_b64_e32 v[10:11], 0
	v_mov_b64_e32 v[12:13], 0
	v_mov_b64_e32 v[14:15], 0
	v_mov_b64_e32 v[16:17], 0
	v_mov_b64_e32 v[18:19], 0
	v_mov_b64_e32 v[20:21], 0
	v_mov_b64_e32 v[22:23], 0
	v_mov_b64_e32 v[24:25], 0
	v_mov_b64_e32 v[26:27], 0
	v_mov_b64_e32 v[28:29], 0
	v_mov_b64_e32 v[30:31], 0
	v_mov_b64_e32 v[32:33], 0
	v_mov_b64_e32 v[34:35], 0
	v_mov_b64_e32 v[36:37], 0
	v_mov_b64_e32 v[38:39], 0
	v_mov_b64_e32 v[40:41], 0
	v_mov_b64_e32 v[42:43], 0
	v_mov_b64_e32 v[44:45], 0
	v_mov_b64_e32 v[46:47], 0
	v_mov_b64_e32 v[48:49], 0
	v_mov_b64_e32 v[50:51], 0
	v_mov_b64_e32 v[52:53], 0
	v_mov_b64_e32 v[54:55], 0
	v_mov_b64_e32 v[56:57], 0
	v_mov_b64_e32 v[58:59], 0
	v_mov_b64_e32 v[60:61], 0
	v_mov_b64_e32 v[62:63], 0
	v_mov_b64_e32 v[64:65], 0
	v_mov_b64_e32 v[66:67], 0
	v_mov_b64_e32 v[68:69], 0
	v_mov_b64_e32 v[70:71], 0
	v_mov_b64_e32 v[72:73], 0
	v_mov_b64_e32 v[74:75], 0
	v_mov_b64_e32 v[76:77], 0
	v_mov_b64_e32 v[78:79], 0
	v_mov_b64_e32 v[80:81], 0
	v_mov_b64_e32 v[82:83], 0
	v_mov_b64_e32 v[84:85], 0
	v_mov_b64_e32 v[86:87], 0
	v_mov_b64_e32 v[88:89], 0
	v_mov_b64_e32 v[90:91], 0
	v_mov_b64_e32 v[92:93], 0
	v_mov_b64_e32 v[94:95], 0
	v_mov_b64_e32 v[96:97], 0
	v_mov_b64_e32 v[98:99], 0
	v_mov_b64_e32 v[100:101], 0
	v_mov_b64_e32 v[102:103], 0
	v_mov_b64_e32 v[104:105], 0
	v_mov_b64_e32 v[106:107], 0
	v_mov_b64_e32 v[108:109], 0
	v_mov_b64_e32 v[110:111], 0
	v_mov_b64_e32 v[112:113], 0
	v_mov_b64_e32 v[114:115], 0
	v_mov_b64_e32 v[116:117], 0
	v_mov_b64_e32 v[118:119], 0
	v_mov_b64_e32 v[120:121], 0
	v_mov_b64_e32 v[122:123], 0
	v_mov_b64_e32 v[124:125], 0
	v_mov_b64_e32 v[126:127], 0
	v_mov_b64_e32 v[128:129], 0
	s_and_b64 vcc, exec, s[16:17]
	s_cbranch_vccnz .LBB0_338
	s_branch .LBB0_339

.LBB0_548:
	v_mov_b64_e32 v[2:3], 0
	v_mov_b64_e32 v[4:5], 0
	v_mov_b64_e32 v[6:7], 0
	v_mov_b64_e32 v[8:9], 0
	v_mov_b64_e32 v[10:11], 0
	v_mov_b64_e32 v[12:13], 0
	v_mov_b64_e32 v[14:15], 0
	v_mov_b64_e32 v[16:17], 0
	v_mov_b64_e32 v[18:19], 0
	v_mov_b64_e32 v[20:21], 0
	v_mov_b64_e32 v[22:23], 0
	v_mov_b64_e32 v[24:25], 0
	v_mov_b64_e32 v[26:27], 0
	v_mov_b64_e32 v[28:29], 0
	v_mov_b64_e32 v[30:31], 0
	v_mov_b64_e32 v[32:33], 0
	v_mov_b64_e32 v[34:35], 0
	v_mov_b64_e32 v[36:37], 0
	v_mov_b64_e32 v[38:39], 0
	v_mov_b64_e32 v[40:41], 0
	v_mov_b64_e32 v[42:43], 0
	v_mov_b64_e32 v[44:45], 0
	v_mov_b64_e32 v[46:47], 0
	v_mov_b64_e32 v[48:49], 0
	v_mov_b64_e32 v[50:51], 0
	v_mov_b64_e32 v[52:53], 0
	v_mov_b64_e32 v[54:55], 0
	v_mov_b64_e32 v[56:57], 0
	v_mov_b64_e32 v[58:59], 0
	v_mov_b64_e32 v[60:61], 0
	v_mov_b64_e32 v[62:63], 0
	v_mov_b64_e32 v[64:65], 0
	v_mov_b64_e32 v[66:67], 0
	v_mov_b64_e32 v[68:69], 0
	v_mov_b64_e32 v[70:71], 0
	v_mov_b64_e32 v[72:73], 0
	v_mov_b64_e32 v[74:75], 0
	v_mov_b64_e32 v[76:77], 0
	v_mov_b64_e32 v[78:79], 0
	v_mov_b64_e32 v[80:81], 0
	v_mov_b64_e32 v[82:83], 0
	v_mov_b64_e32 v[84:85], 0
	v_mov_b64_e32 v[86:87], 0
	v_mov_b64_e32 v[88:89], 0
	v_mov_b64_e32 v[90:91], 0
	v_mov_b64_e32 v[92:93], 0
	v_mov_b64_e32 v[94:95], 0
	v_mov_b64_e32 v[96:97], 0
	v_mov_b64_e32 v[98:99], 0
	v_mov_b64_e32 v[100:101], 0
	v_mov_b64_e32 v[102:103], 0
	v_mov_b64_e32 v[104:105], 0
	v_mov_b64_e32 v[106:107], 0
	v_mov_b64_e32 v[108:109], 0
	v_mov_b64_e32 v[110:111], 0
	v_mov_b64_e32 v[112:113], 0
	v_mov_b64_e32 v[114:115], 0
	v_mov_b64_e32 v[116:117], 0
	v_mov_b64_e32 v[118:119], 0
	v_mov_b64_e32 v[120:121], 0
	v_mov_b64_e32 v[122:123], 0
	v_mov_b64_e32 v[124:125], 0
	v_mov_b64_e32 v[126:127], 0
	v_mov_b64_e32 v[128:129], 0
	s_and_b64 vcc, exec, s[6:7]
	s_cbranch_vccnz .LBB0_544
	s_branch .LBB0_545

.LBB0_852:
	v_mov_b64_e32 v[2:3], 0
	v_mov_b64_e32 v[4:5], 0
	v_mov_b64_e32 v[6:7], 0
	v_mov_b64_e32 v[8:9], 0
	v_mov_b64_e32 v[10:11], 0
	v_mov_b64_e32 v[12:13], 0
	v_mov_b64_e32 v[14:15], 0
	v_mov_b64_e32 v[16:17], 0
	v_mov_b64_e32 v[18:19], 0
	v_mov_b64_e32 v[20:21], 0
	v_mov_b64_e32 v[22:23], 0
	v_mov_b64_e32 v[24:25], 0
	v_mov_b64_e32 v[26:27], 0
	v_mov_b64_e32 v[28:29], 0
	v_mov_b64_e32 v[30:31], 0
	v_mov_b64_e32 v[32:33], 0
	v_mov_b64_e32 v[34:35], 0
	v_mov_b64_e32 v[36:37], 0
	v_mov_b64_e32 v[38:39], 0
	v_mov_b64_e32 v[40:41], 0
	v_mov_b64_e32 v[42:43], 0
	v_mov_b64_e32 v[44:45], 0
	v_mov_b64_e32 v[46:47], 0
	v_mov_b64_e32 v[48:49], 0
	v_mov_b64_e32 v[50:51], 0
	v_mov_b64_e32 v[52:53], 0
	v_mov_b64_e32 v[54:55], 0
	v_mov_b64_e32 v[56:57], 0
	v_mov_b64_e32 v[58:59], 0
	v_mov_b64_e32 v[60:61], 0
	v_mov_b64_e32 v[62:63], 0
	v_mov_b64_e32 v[64:65], 0
	v_mov_b64_e32 v[66:67], 0
	v_mov_b64_e32 v[68:69], 0
	v_mov_b64_e32 v[70:71], 0
	v_mov_b64_e32 v[72:73], 0
	v_mov_b64_e32 v[74:75], 0
	v_mov_b64_e32 v[76:77], 0
	v_mov_b64_e32 v[78:79], 0
	v_mov_b64_e32 v[80:81], 0
	v_mov_b64_e32 v[82:83], 0
	v_mov_b64_e32 v[84:85], 0
	v_mov_b64_e32 v[86:87], 0
	v_mov_b64_e32 v[88:89], 0
	v_mov_b64_e32 v[90:91], 0
	v_mov_b64_e32 v[92:93], 0
	v_mov_b64_e32 v[94:95], 0
	v_mov_b64_e32 v[96:97], 0
	v_mov_b64_e32 v[98:99], 0
	v_mov_b64_e32 v[100:101], 0
	v_mov_b64_e32 v[102:103], 0
	v_mov_b64_e32 v[104:105], 0
	v_mov_b64_e32 v[106:107], 0
	v_mov_b64_e32 v[108:109], 0
	v_mov_b64_e32 v[110:111], 0
	v_mov_b64_e32 v[112:113], 0
	v_mov_b64_e32 v[114:115], 0
	v_mov_b64_e32 v[116:117], 0
	v_mov_b64_e32 v[118:119], 0
	v_mov_b64_e32 v[120:121], 0
	v_mov_b64_e32 v[122:123], 0
	v_mov_b64_e32 v[124:125], 0
	v_mov_b64_e32 v[126:127], 0
	v_mov_b64_e32 v[128:129], 0
	s_and_b64 vcc, exec, s[18:19]
	s_cbranch_vccnz .LBB0_848
	s_branch .LBB0_849

.LBB0_931:
	v_mov_b64_e32 v[2:3], 0
	v_mov_b64_e32 v[4:5], 0
	v_mov_b64_e32 v[6:7], 0
	v_mov_b64_e32 v[8:9], 0
	v_mov_b64_e32 v[10:11], 0
	v_mov_b64_e32 v[12:13], 0
	v_mov_b64_e32 v[14:15], 0
	v_mov_b64_e32 v[16:17], 0
	v_mov_b64_e32 v[18:19], 0
	v_mov_b64_e32 v[20:21], 0
	v_mov_b64_e32 v[22:23], 0
	v_mov_b64_e32 v[24:25], 0
	v_mov_b64_e32 v[26:27], 0
	v_mov_b64_e32 v[28:29], 0
	v_mov_b64_e32 v[30:31], 0
	v_mov_b64_e32 v[32:33], 0
	v_mov_b64_e32 v[34:35], 0
	v_mov_b64_e32 v[36:37], 0
	v_mov_b64_e32 v[38:39], 0
	v_mov_b64_e32 v[40:41], 0
	v_mov_b64_e32 v[42:43], 0
	v_mov_b64_e32 v[44:45], 0
	v_mov_b64_e32 v[46:47], 0
	v_mov_b64_e32 v[48:49], 0
	v_mov_b64_e32 v[50:51], 0
	v_mov_b64_e32 v[52:53], 0
	v_mov_b64_e32 v[54:55], 0
	v_mov_b64_e32 v[56:57], 0
	v_mov_b64_e32 v[58:59], 0
	v_mov_b64_e32 v[60:61], 0
	v_mov_b64_e32 v[62:63], 0
	v_mov_b64_e32 v[64:65], 0
	v_mov_b64_e32 v[66:67], 0
	v_mov_b64_e32 v[68:69], 0
	v_mov_b64_e32 v[70:71], 0
	v_mov_b64_e32 v[72:73], 0
	v_mov_b64_e32 v[74:75], 0
	v_mov_b64_e32 v[76:77], 0
	v_mov_b64_e32 v[78:79], 0
	v_mov_b64_e32 v[80:81], 0
	v_mov_b64_e32 v[82:83], 0
	v_mov_b64_e32 v[84:85], 0
	v_mov_b64_e32 v[86:87], 0
	v_mov_b64_e32 v[88:89], 0
	v_mov_b64_e32 v[90:91], 0
	v_mov_b64_e32 v[92:93], 0
	v_mov_b64_e32 v[94:95], 0
	v_mov_b64_e32 v[96:97], 0
	v_mov_b64_e32 v[98:99], 0
	v_mov_b64_e32 v[100:101], 0
	v_mov_b64_e32 v[102:103], 0
	v_mov_b64_e32 v[104:105], 0
	v_mov_b64_e32 v[106:107], 0
	v_mov_b64_e32 v[108:109], 0
	v_mov_b64_e32 v[110:111], 0
	v_mov_b64_e32 v[112:113], 0
	v_mov_b64_e32 v[114:115], 0
	v_mov_b64_e32 v[116:117], 0
	v_mov_b64_e32 v[118:119], 0
	v_mov_b64_e32 v[120:121], 0
	v_mov_b64_e32 v[122:123], 0
	v_mov_b64_e32 v[124:125], 0
	v_mov_b64_e32 v[126:127], 0
	v_mov_b64_e32 v[128:129], 0
	s_and_b64 vcc, exec, s[12:13]
	s_cbranch_vccnz .LBB0_927
	s_branch .LBB0_928

.LBB0_1161:
	v_mov_b64_e32 v[2:3], 0
	v_mov_b64_e32 v[4:5], 0
	v_mov_b64_e32 v[6:7], 0
	v_mov_b64_e32 v[8:9], 0
	v_mov_b64_e32 v[10:11], 0
	v_mov_b64_e32 v[12:13], 0
	v_mov_b64_e32 v[14:15], 0
	v_mov_b64_e32 v[16:17], 0
	v_mov_b64_e32 v[18:19], 0
	v_mov_b64_e32 v[20:21], 0
	v_mov_b64_e32 v[22:23], 0
	v_mov_b64_e32 v[24:25], 0
	v_mov_b64_e32 v[26:27], 0
	v_mov_b64_e32 v[28:29], 0
	v_mov_b64_e32 v[30:31], 0
	v_mov_b64_e32 v[32:33], 0
	v_mov_b64_e32 v[34:35], 0
	v_mov_b64_e32 v[36:37], 0
	v_mov_b64_e32 v[38:39], 0
	v_mov_b64_e32 v[40:41], 0
	v_mov_b64_e32 v[42:43], 0
	v_mov_b64_e32 v[44:45], 0
	v_mov_b64_e32 v[46:47], 0
	v_mov_b64_e32 v[48:49], 0
	v_mov_b64_e32 v[50:51], 0
	v_mov_b64_e32 v[52:53], 0
	v_mov_b64_e32 v[54:55], 0
	v_mov_b64_e32 v[56:57], 0
	v_mov_b64_e32 v[58:59], 0
	v_mov_b64_e32 v[60:61], 0
	v_mov_b64_e32 v[62:63], 0
	v_mov_b64_e32 v[64:65], 0
	v_mov_b64_e32 v[66:67], 0
	v_mov_b64_e32 v[68:69], 0
	v_mov_b64_e32 v[70:71], 0
	v_mov_b64_e32 v[72:73], 0
	v_mov_b64_e32 v[74:75], 0
	v_mov_b64_e32 v[76:77], 0
	v_mov_b64_e32 v[78:79], 0
	v_mov_b64_e32 v[80:81], 0
	v_mov_b64_e32 v[82:83], 0
	v_mov_b64_e32 v[84:85], 0
	v_mov_b64_e32 v[86:87], 0
	v_mov_b64_e32 v[88:89], 0
	v_mov_b64_e32 v[90:91], 0
	v_mov_b64_e32 v[92:93], 0
	v_mov_b64_e32 v[94:95], 0
	v_mov_b64_e32 v[96:97], 0
	v_mov_b64_e32 v[98:99], 0
	v_mov_b64_e32 v[100:101], 0
	v_mov_b64_e32 v[102:103], 0
	v_mov_b64_e32 v[104:105], 0
	v_mov_b64_e32 v[106:107], 0
	v_mov_b64_e32 v[108:109], 0
	v_mov_b64_e32 v[110:111], 0
	v_mov_b64_e32 v[112:113], 0
	v_mov_b64_e32 v[114:115], 0
	v_mov_b64_e32 v[116:117], 0
	v_mov_b64_e32 v[118:119], 0
	v_mov_b64_e32 v[120:121], 0
	v_mov_b64_e32 v[122:123], 0
	v_mov_b64_e32 v[124:125], 0
	v_mov_b64_e32 v[126:127], 0
	v_mov_b64_e32 v[128:129], 0
	s_and_b64 vcc, exec, s[10:11]
	s_cbranch_vccnz .LBB0_1157
	s_branch .LBB0_1158
